# SSD_PREP prefix sum of dt*A via 6 DPP adds (row_shr 1/2/4/8, row_bcast 15/31) instead of 6 dependent ds_bpermute round trips; on top of block-parallel LRU scan
# speedup vs baseline: 1.0173x; 1.0001x over previous
.LBB0_747:
	v_lshrrev_b32_e32 v202, 4, v201
	s_waitcnt vmcnt(2)
	v_mul_f32_e32 v2, 0x3fb8aa3b, v2
	s_lshl_b32 s54, s76, 4
	v_exp_f32_e32 v204, v2
	v_lshl_or_b32 v2, v202, 2, s54
	v_and_b32_e32 v105, 15, v1
	s_lshl_b32 s5, s5, 16
	v_mul_u32_u24_e32 v6, 0x48, v2
	s_add_i32 s77, s5, 0
	v_or_b32_e32 v7, v6, v105
	v_lshl_add_u32 v7, v7, 1, s77
	ds_write_b16 v7, v0 offset:46080
	v_mad_u32_u24 v7, v2, s86, s86
	v_add_u32_e32 v8, v7, v105
	v_lshl_add_u32 v8, v8, 1, s77
	ds_write_b16 v8, v0 offset:46080
	v_mad_u32_u24 v8, v2, s86, v234
	v_or_b32_e32 v9, v8, v105
	v_lshl_add_u32 v9, v9, 1, s77
	v_or_b32_e32 v3, 16, v105
	ds_write_b16 v9, v0 offset:46080
	v_mad_u32_u24 v9, v2, s86, v235
	v_add_u32_e32 v10, v9, v105
	v_or_b32_e32 v6, v6, v3
	v_lshl_add_u32 v10, v10, 1, s77
	v_lshl_add_u32 v6, v6, 1, s77
	ds_write_b16 v10, v0 offset:46080
	ds_write_b16 v6, v0 offset:46080
	v_add_u32_e32 v6, v7, v3
	v_lshl_add_u32 v6, v6, 1, s77
	ds_write_b16 v6, v0 offset:46080
	v_add_u32_e32 v6, v8, v3
	v_add_u32_e32 v3, v9, v3
	v_or_b32_e32 v4, 32, v105
	v_lshl_add_u32 v3, v3, 1, s77
	ds_write_b16 v3, v0 offset:46080
	v_mad_u32_u24 v3, v2, s86, v4
	v_lshl_add_u32 v6, v6, 1, s77
	v_lshl_add_u32 v3, v3, 1, s77
	ds_write_b16 v6, v0 offset:46080
	ds_write_b16 v3, v0 offset:46080
	v_add_u32_e32 v3, v7, v4
	v_lshl_add_u32 v3, v3, 1, s77
	ds_write_b16 v3, v0 offset:46080
	v_add_u32_e32 v3, v8, v4
	v_or_b32_e32 v5, 48, v105
	v_lshl_add_u32 v3, v3, 1, s77
	ds_write_b16 v3, v0 offset:46080
	v_add_u32_e32 v3, v9, v4
	v_mad_u32_u24 v2, v2, s86, v5
	v_lshl_add_u32 v3, v3, 1, s77
	v_lshl_add_u32 v2, v2, 1, s77
	ds_write_b16 v3, v0 offset:46080
	ds_write_b16 v2, v0 offset:46080
	v_add_u32_e32 v2, v7, v5
	v_lshl_add_u32 v2, v2, 1, s77
	ds_write_b16 v2, v0 offset:46080
	v_add_u32_e32 v2, v8, v5
	v_lshl_add_u32 v2, v2, 1, s77
	ds_write_b16 v2, v0 offset:46080
	v_add_u32_e32 v2, v9, v5
	v_cndmask_b32_e64 v3, 0, 1, s[10:11]
	v_lshl_add_u32 v2, v2, 1, s77
	v_cmp_ne_u32_e64 s[8:9], 1, v3
	s_andn2_b64 vcc, exec, s[10:11]
	ds_write_b16 v2, v0 offset:46080
	s_cbranch_vccnz .LBB0_749
	s_waitcnt vmcnt(0)
	v_add_f32_e32 v2, v189, v203
	v_mul_f32_e64 v3, |v2|, s87
	v_exp_f32_e32 v3, v3
	v_max_f32_e32 v2, 0, v2
	v_add_f32_e32 v3, 1.0, v3
	v_cmp_gt_f32_e32 vcc, s84, v3
	s_nop 1
	v_cndmask_b32_e64 v4, 0, 32, vcc
	v_ldexp_f32 v3, v3, v4
	v_log_f32_e32 v3, v3
	v_cndmask_b32_e32 v4, 0, v232, vcc
	v_mul_f32_e32 v5, 0x3f317217, v3
	v_fma_f32 v5, v3, s80, -v5
	v_fmac_f32_e32 v5, 0x3377d1cf, v3
	v_fmac_f32_e32 v5, 0x3f317217, v3
	v_cmp_lt_f32_e64 vcc, |v3|, s81
	s_nop 1
	v_cndmask_b32_e32 v3, v3, v5, vcc
	v_sub_f32_e32 v3, v3, v4
	v_cmp_ne_u32_e32 vcc, 0, v201
	v_add_f32_e32 v2, v2, v3
	v_mul_f32_e64 v3, v2, -v204
	s_nop 1
	v_add_f32_dpp v3, v3, v3 row_shr:1 row_mask:0xf bank_mask:0xf
	s_nop 1
	v_add_f32_dpp v3, v3, v3 row_shr:2 row_mask:0xf bank_mask:0xf
	s_nop 1
	v_add_f32_dpp v3, v3, v3 row_shr:4 row_mask:0xf bank_mask:0xf
	s_nop 1
	v_add_f32_dpp v3, v3, v3 row_shr:8 row_mask:0xf bank_mask:0xf
	s_nop 1
	v_add_f32_dpp v3, v3, v3 row_bcast:15 row_mask:0xa bank_mask:0xf
	s_nop 1
	v_add_f32_dpp v3, v3, v3 row_bcast:31 row_mask:0xc bank_mask:0xf
	v_cmp_gt_u32_e64 s[12:13], 2, v201
	v_cmp_gt_u32_e32 vcc, 4, v201
	v_cmp_gt_u32_e64 s[12:13], 8, v201
	v_cmp_gt_u32_e32 vcc, 16, v201
	v_and_b32_e32 v5, 0x7c, v5
	v_cmp_gt_u32_e32 vcc, 32, v201
	v_lshl_add_u32 v4, v201, 2, s77
	v_readlane_b32 s5, v3, 63
	s_nop 1
	v_sub_f32_e32 v5, s5, v3
	v_fma_f32 v5, v2, -v204, v5
	v_cndmask_b32_e64 v3, v5, v3, s[6:7]
	ds_write2st64_b32 v4, v2, v3 offset0:252 offset1:253

.LBB0_896:
	v_add_u32_e32 v1, 48, v105
	v_add_u32_e32 v3, 32, v105
	s_andn2_b64 vcc, exec, s[10:11]
	v_add_u32_e32 v64, 16, v105
	s_cbranch_vccnz .LBB0_899
	s_xor_b32 s5, s51, 1
	v_add_u32_e32 v65, s54, v2
	s_mul_i32 s10, s5, 0x2400
	v_mul_lo_u32 v65, v65, s86
	s_add_i32 s10, s77, s10
	v_add_u32_e32 v67, v65, v105
	v_cvt_pk_bf16_f32 v66, v52, s0
	v_lshl_add_u32 v67, v67, 1, s10
	ds_write_b16 v67, v66 offset:46080
	v_add_u32_e32 v67, 0x48, v65
	v_add_u32_e32 v68, v67, v105
	v_cvt_pk_bf16_f32 v66, v53, s0
	v_lshl_add_u32 v68, v68, 1, s10
	ds_write_b16 v68, v66 offset:46080
	v_add_u32_e32 v68, 0x90, v65
	v_add_u32_e32 v69, v68, v105
	v_cvt_pk_bf16_f32 v66, v54, s0
	v_lshl_add_u32 v69, v69, 1, s10
	ds_write_b16 v69, v66 offset:46080
	v_add_u32_e32 v69, 0xd8, v65
	v_add_u32_e32 v70, v69, v105
	v_cvt_pk_bf16_f32 v66, v55, s0
	v_lshl_add_u32 v70, v70, 1, s10
	ds_write_b16 v70, v66 offset:46080
	v_add_u32_e32 v70, v65, v64
	v_cvt_pk_bf16_f32 v66, v56, s0
	v_lshl_add_u32 v70, v70, 1, s10
	ds_write_b16 v70, v66 offset:46080
	v_add_u32_e32 v70, v67, v64
	v_cvt_pk_bf16_f32 v66, v57, s0
	v_lshl_add_u32 v70, v70, 1, s10
	ds_write_b16 v70, v66 offset:46080
	v_add_u32_e32 v70, v68, v64
	v_cvt_pk_bf16_f32 v66, v58, s0
	v_lshl_add_u32 v70, v70, 1, s10
	ds_write_b16 v70, v66 offset:46080
	v_add_u32_e32 v70, v69, v64
	v_cvt_pk_bf16_f32 v66, v59, s0
	v_lshl_add_u32 v70, v70, 1, s10
	ds_write_b16 v70, v66 offset:46080
	v_add_u32_e32 v70, v65, v3
	v_cvt_pk_bf16_f32 v66, v44, s0
	v_lshl_add_u32 v70, v70, 1, s10
	ds_write_b16 v70, v66 offset:46080
	v_add_u32_e32 v70, v67, v3
	v_cvt_pk_bf16_f32 v66, v45, s0
	v_lshl_add_u32 v70, v70, 1, s10
	ds_write_b16 v70, v66 offset:46080
	v_add_u32_e32 v70, v68, v3
	v_cvt_pk_bf16_f32 v66, v46, s0
	v_lshl_add_u32 v70, v70, 1, s10
	ds_write_b16 v70, v66 offset:46080
	v_add_u32_e32 v70, v69, v3
	v_cvt_pk_bf16_f32 v66, v47, s0
	v_lshl_add_u32 v70, v70, 1, s10
	v_add_u32_e32 v65, v65, v1
	ds_write_b16 v70, v66 offset:46080
	v_cvt_pk_bf16_f32 v66, v36, s0
	v_lshl_add_u32 v65, v65, 1, s10
	ds_write_b16 v65, v66 offset:46080
	v_add_u32_e32 v66, v67, v1
	v_cvt_pk_bf16_f32 v65, v37, s0
	v_lshl_add_u32 v66, v66, 1, s10
	ds_write_b16 v66, v65 offset:46080
	v_add_u32_e32 v66, v68, v1
	v_cvt_pk_bf16_f32 v65, v38, s0
	v_lshl_add_u32 v66, v66, 1, s10
	ds_write_b16 v66, v65 offset:46080
	v_add_u32_e32 v66, v69, v1
	v_cvt_pk_bf16_f32 v65, v39, s0
	v_lshl_add_u32 v66, v66, 1, s10
	s_and_b64 vcc, exec, s[8:9]
	ds_write_b16 v66, v65 offset:46080
	s_cbranch_vccnz .LBB0_899
	s_waitcnt vmcnt(4)
	v_add_f32_e32 v65, v189, v203
	v_mul_f32_e64 v66, |v65|, s87
	v_exp_f32_e32 v66, v66
	v_max_f32_e32 v65, 0, v65
	s_lshl_b32 s5, s5, 9
	s_add_i32 s5, s77, s5
	v_add_f32_e32 v66, 1.0, v66
	v_cmp_gt_f32_e32 vcc, s84, v66
	s_nop 1
	v_cndmask_b32_e64 v67, 0, 32, vcc
	v_ldexp_f32 v66, v66, v67
	v_log_f32_e32 v66, v66
	v_cndmask_b32_e32 v67, 0, v232, vcc
	v_mul_f32_e32 v68, 0x3f317217, v66
	v_fma_f32 v68, v66, s80, -v68
	v_fmac_f32_e32 v68, 0x3377d1cf, v66
	v_fmac_f32_e32 v68, 0x3f317217, v66
	v_cmp_lt_f32_e64 vcc, |v66|, s81
	s_nop 1
	v_cndmask_b32_e32 v66, v66, v68, vcc
	v_sub_f32_e32 v66, v66, v67
	v_cmp_lt_i32_e32 vcc, 0, v201
	v_add_f32_e32 v65, v65, v66
	v_mul_f32_e64 v66, v65, -v204
	s_nop 1
	v_add_f32_dpp v66, v66, v66 row_shr:1 row_mask:0xf bank_mask:0xf
	s_nop 1
	v_add_f32_dpp v66, v66, v66 row_shr:2 row_mask:0xf bank_mask:0xf
	s_nop 1
	v_add_f32_dpp v66, v66, v66 row_shr:4 row_mask:0xf bank_mask:0xf
	s_nop 1
	v_add_f32_dpp v66, v66, v66 row_shr:8 row_mask:0xf bank_mask:0xf
	s_nop 1
	v_add_f32_dpp v66, v66, v66 row_bcast:15 row_mask:0xa bank_mask:0xf
	s_nop 1
	v_add_f32_dpp v66, v66, v66 row_bcast:31 row_mask:0xc bank_mask:0xf
	v_lshl_add_u32 v67, v201, 2, s5
	v_readlane_b32 s10, v66, 63
	s_nop 1
	v_sub_f32_e32 v68, s10, v66
	v_fma_f32 v68, v65, -v204, v68
	v_cndmask_b32_e64 v66, v68, v66, s[6:7]
	ds_write2st64_b32 v67, v65, v66 offset0:252 offset1:253

.LBB0_925:
	s_lshl_b32 s12, s51, 16
	v_mul_u32_u24_e32 v23, 0x48, v2
	s_add_i32 s51, s12, 0
	v_or_b32_e32 v24, v23, v189
	s_waitcnt vmcnt(15)
	v_cvt_pk_bf16_f32 v22, v4, s0
	v_lshl_add_u32 v24, v24, 1, s51
	ds_write_b16 v24, v22 offset:46080
	v_mad_u32_u24 v24, v2, s86, s86
	v_add_u32_e32 v25, v24, v189
	s_waitcnt vmcnt(14)
	v_cvt_pk_bf16_f32 v22, v5, s0
	v_lshl_add_u32 v25, v25, 1, s51
	ds_write_b16 v25, v22 offset:46080
	v_mad_u32_u24 v25, v2, s86, v234
	v_or_b32_e32 v26, v25, v189
	s_waitcnt vmcnt(7)
	v_cvt_pk_bf16_f32 v22, v6, s0
	v_lshl_add_u32 v26, v26, 1, s51
	v_mul_f32_e32 v3, 0x3fb8aa3b, v3
	ds_write_b16 v26, v22 offset:46080
	v_mad_u32_u24 v26, v2, s86, v235
	v_exp_f32_e32 v205, v3
	v_or_b32_e32 v3, 16, v189
	v_add_u32_e32 v27, v26, v189
	s_waitcnt vmcnt(6)
	v_cvt_pk_bf16_f32 v22, v7, s0
	v_lshl_add_u32 v27, v27, 1, s51
	v_or_b32_e32 v23, v23, v3
	ds_write_b16 v27, v22 offset:46080
	v_cvt_pk_bf16_f32 v22, v12, s0
	v_lshl_add_u32 v23, v23, 1, s51
	ds_write_b16 v23, v22 offset:46080
	v_add_u32_e32 v23, v24, v3
	v_cvt_pk_bf16_f32 v22, v13, s0
	v_lshl_add_u32 v23, v23, 1, s51
	ds_write_b16 v23, v22 offset:46080
	v_add_u32_e32 v23, v25, v3
	s_waitcnt vmcnt(5)
	v_cvt_pk_bf16_f32 v22, v14, s0
	v_lshl_add_u32 v23, v23, 1, s51
	v_add_u32_e32 v3, v26, v3
	v_or_b32_e32 v20, 32, v189
	ds_write_b16 v23, v22 offset:46080
	s_waitcnt vmcnt(4)
	v_cvt_pk_bf16_f32 v22, v15, s0
	v_lshl_add_u32 v3, v3, 1, s51
	ds_write_b16 v3, v22 offset:46080
	v_mad_u32_u24 v22, v2, s86, v20
	v_cvt_pk_bf16_f32 v3, v16, s0
	v_lshl_add_u32 v22, v22, 1, s51
	ds_write_b16 v22, v3 offset:46080
	v_add_u32_e32 v22, v24, v20
	v_cvt_pk_bf16_f32 v3, v17, s0
	v_lshl_add_u32 v22, v22, 1, s51
	ds_write_b16 v22, v3 offset:46080
	v_add_u32_e32 v22, v25, v20
	v_or_b32_e32 v21, 48, v189
	s_waitcnt vmcnt(3)
	v_cvt_pk_bf16_f32 v3, v18, s0
	v_lshl_add_u32 v22, v22, 1, s51
	v_add_u32_e32 v20, v26, v20
	ds_write_b16 v22, v3 offset:46080
	s_waitcnt vmcnt(2)
	v_cvt_pk_bf16_f32 v3, v19, s0
	v_lshl_add_u32 v20, v20, 1, s51
	v_mad_u32_u24 v2, v2, s86, v21
	ds_write_b16 v20, v3 offset:46080
	v_cvt_pk_bf16_f32 v3, v8, s0
	v_lshl_add_u32 v2, v2, 1, s51
	ds_write_b16 v2, v3 offset:46080
	v_add_u32_e32 v3, v24, v21
	v_cvt_pk_bf16_f32 v2, v9, s0
	v_lshl_add_u32 v3, v3, 1, s51
	ds_write_b16 v3, v2 offset:46080
	v_add_u32_e32 v3, v25, v21
	s_waitcnt vmcnt(0)
	v_cvt_pk_bf16_f32 v2, v10, s0
	v_lshl_add_u32 v3, v3, 1, s51
	ds_write_b16 v3, v2 offset:46080
	v_add_u32_e32 v3, v26, v21
	v_cvt_pk_bf16_f32 v2, v11, s0
	v_lshl_add_u32 v3, v3, 1, s51
	s_and_b64 vcc, exec, s[8:9]
	ds_write_b16 v3, v2 offset:46080
	s_cbranch_vccnz .LBB0_927
	v_add_f32_e32 v2, v201, v204
	v_mul_f32_e64 v3, |v2|, s87
	v_exp_f32_e32 v3, v3
	v_max_f32_e32 v2, 0, v2
	v_add_f32_e32 v3, 1.0, v3
	v_cmp_gt_f32_e32 vcc, s84, v3
	s_nop 1
	v_cndmask_b32_e64 v20, 0, 32, vcc
	v_ldexp_f32 v3, v3, v20
	v_log_f32_e32 v3, v3
	v_cndmask_b32_e32 v20, 0, v232, vcc
	v_mul_f32_e32 v21, 0x3f317217, v3
	v_fma_f32 v21, v3, s80, -v21
	v_fmac_f32_e32 v21, 0x3377d1cf, v3
	v_fmac_f32_e32 v21, 0x3f317217, v3
	v_cmp_lt_f32_e64 vcc, |v3|, s81
	s_nop 1
	v_cndmask_b32_e32 v3, v3, v21, vcc
	v_sub_f32_e32 v3, v3, v20
	v_cmp_ne_u32_e32 vcc, 0, v203
	v_add_f32_e32 v2, v2, v3
	v_mul_f32_e64 v3, v2, -v205
	s_nop 1
	v_add_f32_dpp v3, v3, v3 row_shr:1 row_mask:0xf bank_mask:0xf
	s_nop 1
	v_add_f32_dpp v3, v3, v3 row_shr:2 row_mask:0xf bank_mask:0xf
	s_nop 1
	v_add_f32_dpp v3, v3, v3 row_shr:4 row_mask:0xf bank_mask:0xf
	s_nop 1
	v_add_f32_dpp v3, v3, v3 row_shr:8 row_mask:0xf bank_mask:0xf
	s_nop 1
	v_add_f32_dpp v3, v3, v3 row_bcast:15 row_mask:0xa bank_mask:0xf
	s_nop 1
	v_add_f32_dpp v3, v3, v3 row_bcast:31 row_mask:0xc bank_mask:0xf
	v_cmp_gt_u32_e64 s[12:13], 2, v203
	v_cmp_gt_u32_e32 vcc, 4, v203
	v_cmp_gt_u32_e64 s[12:13], 8, v203
	v_cmp_gt_u32_e32 vcc, 16, v203
	v_and_b32_e32 v21, 0x7c, v21
	v_cmp_gt_u32_e32 vcc, 32, v203
	v_lshl_add_u32 v20, v203, 2, s51
	v_readlane_b32 s12, v3, 63
	s_nop 1
	v_sub_f32_e32 v21, s12, v3
	v_fma_f32 v21, v2, -v205, v21
	v_cndmask_b32_e64 v3, v21, v3, s[6:7]
	ds_write2st64_b32 v20, v2, v3 offset0:252 offset1:253

.LBB0_1075:
	s_andn2_b64 vcc, exec, s[10:11]
	s_cbranch_vccnz .LBB0_938
	s_xor_b32 s4, s52, 1
	v_add_u32_e32 v2, s49, v2
	s_mul_i32 s5, s4, 0x2400
	v_mul_lo_u32 v2, v2, s86
	s_add_i32 s5, s51, s5
	v_add_u32_e32 v66, v2, v189
	v_cvt_pk_bf16_f32 v65, v4, s0
	v_lshl_add_u32 v66, v66, 1, s5
	ds_write_b16 v66, v65 offset:46080
	v_add_u32_e32 v66, 0x48, v2
	v_add_u32_e32 v67, v66, v189
	v_cvt_pk_bf16_f32 v65, v5, s0
	v_lshl_add_u32 v67, v67, 1, s5
	ds_write_b16 v67, v65 offset:46080
	v_add_u32_e32 v67, 0x90, v2
	v_add_u32_e32 v68, v67, v189
	v_cvt_pk_bf16_f32 v65, v6, s0
	v_lshl_add_u32 v68, v68, 1, s5
	ds_write_b16 v68, v65 offset:46080
	v_add_u32_e32 v68, 0xd8, v2
	v_add_u32_e32 v69, v68, v189
	v_add_u32_e32 v64, 16, v189
	v_cvt_pk_bf16_f32 v65, v7, s0
	v_lshl_add_u32 v69, v69, 1, s5
	ds_write_b16 v69, v65 offset:46080
	v_add_u32_e32 v69, v2, v64
	v_cvt_pk_bf16_f32 v65, v12, s0
	v_lshl_add_u32 v69, v69, 1, s5
	ds_write_b16 v69, v65 offset:46080
	v_add_u32_e32 v69, v66, v64
	v_cvt_pk_bf16_f32 v65, v13, s0
	v_lshl_add_u32 v69, v69, 1, s5
	ds_write_b16 v69, v65 offset:46080
	v_add_u32_e32 v69, v67, v64
	v_cvt_pk_bf16_f32 v65, v14, s0
	v_lshl_add_u32 v69, v69, 1, s5
	v_add_u32_e32 v64, v68, v64
	v_add_u32_e32 v3, 32, v189
	ds_write_b16 v69, v65 offset:46080
	v_cvt_pk_bf16_f32 v65, v15, s0
	v_lshl_add_u32 v64, v64, 1, s5
	ds_write_b16 v64, v65 offset:46080
	v_add_u32_e32 v65, v2, v3
	v_cvt_pk_bf16_f32 v64, v16, s0
	v_lshl_add_u32 v65, v65, 1, s5
	ds_write_b16 v65, v64 offset:46080
	v_add_u32_e32 v65, v66, v3
	v_cvt_pk_bf16_f32 v64, v17, s0
	v_lshl_add_u32 v65, v65, 1, s5
	ds_write_b16 v65, v64 offset:46080
	v_add_u32_e32 v65, v67, v3
	v_add_u32_e32 v1, 48, v189
	v_cvt_pk_bf16_f32 v64, v18, s0
	v_lshl_add_u32 v65, v65, 1, s5
	v_add_u32_e32 v3, v68, v3
	ds_write_b16 v65, v64 offset:46080
	v_cvt_pk_bf16_f32 v64, v19, s0
	v_lshl_add_u32 v3, v3, 1, s5
	v_add_u32_e32 v2, v2, v1
	ds_write_b16 v3, v64 offset:46080
	v_cvt_pk_bf16_f32 v3, v8, s0
	v_lshl_add_u32 v2, v2, 1, s5
	ds_write_b16 v2, v3 offset:46080
	v_add_u32_e32 v3, v66, v1
	v_cvt_pk_bf16_f32 v2, v9, s0
	v_lshl_add_u32 v3, v3, 1, s5
	ds_write_b16 v3, v2 offset:46080
	v_add_u32_e32 v3, v67, v1
	v_cvt_pk_bf16_f32 v2, v10, s0
	v_lshl_add_u32 v3, v3, 1, s5
	v_add_u32_e32 v1, v68, v1
	ds_write_b16 v3, v2 offset:46080
	v_cvt_pk_bf16_f32 v2, v11, s0
	v_lshl_add_u32 v1, v1, 1, s5
	s_and_b64 vcc, exec, s[8:9]
	ds_write_b16 v1, v2 offset:46080
	s_cbranch_vccnz .LBB0_938
	s_waitcnt vmcnt(4)
	v_add_f32_e32 v1, v201, v204
	v_mul_f32_e64 v2, |v1|, s87
	v_exp_f32_e32 v2, v2
	v_max_f32_e32 v1, 0, v1
	s_lshl_b32 s4, s4, 9
	s_add_i32 s4, s51, s4
	v_add_f32_e32 v2, 1.0, v2
	v_cmp_gt_f32_e32 vcc, s84, v2
	s_nop 1
	v_cndmask_b32_e64 v3, 0, 32, vcc
	v_ldexp_f32 v2, v2, v3
	v_log_f32_e32 v2, v2
	v_cndmask_b32_e32 v3, 0, v232, vcc
	v_mul_f32_e32 v64, 0x3f317217, v2
	v_fma_f32 v64, v2, s80, -v64
	v_fmac_f32_e32 v64, 0x3377d1cf, v2
	v_fmac_f32_e32 v64, 0x3f317217, v2
	v_cmp_lt_f32_e64 vcc, |v2|, s81
	s_nop 1
	v_cndmask_b32_e32 v2, v2, v64, vcc
	v_sub_f32_e32 v2, v2, v3
	v_cmp_lt_i32_e32 vcc, 0, v203
	v_add_f32_e32 v1, v1, v2
	v_mul_f32_e64 v2, v1, -v205
	s_nop 1
	v_add_f32_dpp v2, v2, v2 row_shr:1 row_mask:0xf bank_mask:0xf
	s_nop 1
	v_add_f32_dpp v2, v2, v2 row_shr:2 row_mask:0xf bank_mask:0xf
	s_nop 1
	v_add_f32_dpp v2, v2, v2 row_shr:4 row_mask:0xf bank_mask:0xf
	s_nop 1
	v_add_f32_dpp v2, v2, v2 row_shr:8 row_mask:0xf bank_mask:0xf
	s_nop 1
	v_add_f32_dpp v2, v2, v2 row_bcast:15 row_mask:0xa bank_mask:0xf
	s_nop 1
	v_add_f32_dpp v2, v2, v2 row_bcast:31 row_mask:0xc bank_mask:0xf
	v_lshl_add_u32 v3, v203, 2, s4
	v_readlane_b32 s5, v2, 63
	s_nop 1
	v_sub_f32_e32 v64, s5, v2
	v_fma_f32 v64, v1, -v205, v64
	v_cndmask_b32_e64 v2, v64, v2, s[6:7]
	ds_write2st64_b32 v3, v1, v2 offset0:252 offset1:253
	s_branch .LBB0_938
